# phase 3: half of the workgroups run the neighbourhood attention before the HGRN2 state pass (complementary power / latency overlap)
# baseline (speedup 1.0000x reference)
.LBB0_363:
	s_waitcnt vmcnt(0)
	s_barrier
	s_cmp_lg_u32 s87, 0x100
	s_cbranch_scc1 .Ltt2_0_done
	s_cmp_lt_u32 s96, 128
	s_cbranch_scc1 .Ltt2_0_done
	s_cmp_ge_u32 s96, 256
	s_cbranch_scc1 .Ltt2_0_done
	s_sub_u32 s20, s96, 128
	s_lshl_b32 s20, s20, 3
	s_add_u32 s20, s20, s93
	s_movk_i32 s23, 1024
	v_mbcnt_hi_u32_b32 v0, -1, v212
	v_and_b32_e32 v0, 63, v0
	v_lshrrev_b32_e32 v1, 3, v0
	v_and_b32_e32 v2, 7, v0
	s_lshl_b32 s25, s93, 14
	v_mul_u32_u24_e32 v3, 0x84, v1
	v_mul_u32_u24_e32 v4, 0x420, v2
	v_lshlrev_b32_e32 v2, 4, v2
	v_add3_u32 v3, v3, v2, s25
	v_lshl_add_u32 v4, v1, 2, v4
	v_add_u32_e32 v4, s25, v4
	v_and_b32_e32 v7, 4, v1
	v_and_b32_e32 v5, 3, v1
	v_lshl_add_u32 v7, v7, 1, v5
	v_readlane_b32 s62, v245, 0
	v_readlane_b32 s63, v245, 1
	s_add_u32 s64, s76, 0x4989000
	s_addc_u32 s65, s77, 0
	v_readlane_b32 s66, v244, 21
	v_readlane_b32 s67, v244, 22
	s_add_u32 s68, s76, 0x8989000
	s_addc_u32 s69, s77, 0
	s_cmp_ge_u32 s20, 12288
	s_cbranch_scc1 .Ltt2_0_done
	s_cmp_lt_u32 s20, 8192
	s_cbranch_scc1 .Ltt2_0_r1_s0
	s_sub_u32 s25, s20, 8192
	s_lshr_b32 s27, s25, 6
	s_and_b32 s31, s25, 63
	s_mul_i32 s35, s27, 0x80000
	s_lshl_b32 s41, s31, 7
	s_add_u32 s35, s35, s41
	s_add_u32 s0, s66, s35
	s_addc_u32 s1, s67, 0
	s_mul_i32 s35, s31, 0x80000
	s_lshl_b32 s41, s27, 7
	s_add_u32 s35, s35, s41
	s_add_u32 s2, s68, s35
	s_addc_u32 s3, s69, 0
	s_mov_b32 s5, 0x2000
	s_mov_b32 s6, 0x10000
	s_mov_b32 s7, 0x4000
	s_branch .Ltt2_0_r1_e

.LBB0_418:
	s_bfe_u32 s100, s96, 0x10003
	s_cmp_lt_i32 s78, 4
	s_cselect_b64 s[0:1], -1, 0
	s_cmp_gt_i32 s79, 3
	s_cselect_b64 s[2:3], -1, 0
	s_and_b64 s[0:1], s[0:1], s[2:3]
	s_andn2_b64 vcc, exec, s[0:1]
	v_writelane_b32 v244, s87, 53
	s_mov_b32 s0, s96
	v_writelane_b32 v244, s0, 54
	s_nop 1
	v_writelane_b32 v244, s1, 55
	v_writelane_b32 v244, s92, 56
	v_writelane_b32 v244, s93, 57
	v_writelane_b32 v244, s76, 58
	s_nop 1
	v_writelane_b32 v244, s77, 59
	v_writelane_b32 v244, s78, 60
	v_writelane_b32 v244, s79, 61
	s_cbranch_vccnz .LBB0_551
.Lp3_body:
	s_add_u32 s88, s76, 0x13589000
	s_addc_u32 s89, s77, 0
	v_readlane_b32 s0, v244, 0
	s_cmpk_lt_i32 s0, 0x100
	s_waitcnt vmcnt(0)
	v_mbcnt_hi_u32_b32 v0, -1, v212
	s_cselect_b64 s[2:3], -1, 0
	s_and_b32 s0, s92, 0xffffffc0
	s_and_b64 vcc, exec, s[2:3]
	v_and_b32_e32 v58, 63, v0
	v_writelane_b32 v244, s0, 62
	s_cmp_eq_u32 s100, 1
	s_cbranch_scc1 .Lp3_noh
	s_cbranch_vccnz .LBB0_481
.Lp3_noh:
	v_and_b32_e32 v179, 63, v0
	v_or_b32_e32 v178, s0, v179
	v_and_b32_e32 v32, 31, v0
	v_lshlrev_b32_e32 v33, 2, v32
	s_cbranch_execz .LBB0_482
	s_andn2_b64 vcc, exec, s[2:3]
	s_cbranch_vccnz .LBB0_496

.LBB0_494:
	v_readlane_b32 s76, v244, 58
	v_readlane_b32 s77, v244, 59
	v_readlane_b32 s78, v244, 60
	v_readlane_b32 s79, v244, 61
	v_readlane_b32 s95, v244, 63
	v_readlane_b32 s92, v244, 56
	v_readlane_b32 s93, v244, 57
	s_cmp_eq_u32 s100, 1
	s_cbranch_scc0 .Lp3_fin
	s_mov_b32 s100, 2
	s_branch .Lp3_body
.Lp3_fin:
	s_cmp_lt_i32 s79, 5
	s_cbranch_scc1 .LBB0_551
	s_branch .LBB0_497
.LBB0_495:
	v_mov_b32_e32 v179, v58
	s_cmp_eq_u32 s100, 2
	s_cbranch_scc1 .LBB0_496
	s_andn2_b64 vcc, exec, s[2:3]
	s_cbranch_vccz .LBB0_422

.LBB0_832:
	s_waitcnt vmcnt(0)
	s_barrier
	s_cmp_lg_u32 s87, 0x100
	s_cbranch_scc1 .Ltt7_0_done
	s_cmp_lt_u32 s96, 128
	s_cbranch_scc1 .Ltt7_0_done
	s_cmp_ge_u32 s96, 256
	s_cbranch_scc1 .Ltt7_0_done
	s_sub_u32 s20, s96, 128
	s_lshl_b32 s20, s20, 3
	s_add_u32 s20, s20, s93
	s_movk_i32 s23, 1024
	v_mbcnt_hi_u32_b32 v0, -1, v212
	v_and_b32_e32 v0, 63, v0
	v_lshrrev_b32_e32 v1, 3, v0
	v_and_b32_e32 v2, 7, v0
	s_lshl_b32 s25, s93, 14
	v_mul_u32_u24_e32 v3, 0x84, v1
	v_mul_u32_u24_e32 v4, 0x420, v2
	v_lshlrev_b32_e32 v2, 4, v2
	v_add3_u32 v3, v3, v2, s25
	v_lshl_add_u32 v4, v1, 2, v4
	v_add_u32_e32 v4, s25, v4
	v_and_b32_e32 v7, 4, v1
	v_and_b32_e32 v5, 3, v1
	v_lshl_add_u32 v7, v7, 1, v5
	v_readlane_b32 s62, v244, 21
	v_readlane_b32 s63, v244, 22
	s_add_u32 s64, s76, 0x8989000
	s_addc_u32 s65, s77, 0
	v_readlane_b32 s66, v245, 0
	v_readlane_b32 s67, v245, 1
	s_add_u32 s68, s76, 0x6989000
	s_addc_u32 s69, s77, 0
	s_nop 0
	s_add_u32 s66, s66, 0x4000000
	s_addc_u32 s67, s67, 0
	s_cmp_ge_u32 s20, 12288
	s_cbranch_scc1 .Ltt7_0_done
	s_cmp_lt_u32 s20, 4096
	s_cbranch_scc1 .Ltt7_0_r1_s0
	s_sub_u32 s25, s20, 4096
	s_lshr_b32 s27, s25, 8
	s_and_b32 s31, s25, 255
	s_mul_i32 s35, s27, 0x200000
	s_lshl_b32 s41, s31, 7
	s_add_u32 s35, s35, s41
	s_add_u32 s0, s66, s35
	s_addc_u32 s1, s67, 0
	s_mul_i32 s35, s31, 0x20000
	s_lshl_b32 s41, s27, 7
	s_add_u32 s35, s35, s41
	s_add_u32 s2, s68, s35
	s_addc_u32 s3, s69, 0
	s_mov_b32 s5, 0x8000
	s_mov_b32 s6, 0x40000
	s_mov_b32 s7, 0x1000
	s_branch .Ltt7_0_r1_e
